# attention loop half-step 1: row-max/rescale chain + exp2 of 16 scores issued inside PV MFMA gaps on the unmasked path (on top of v11 stack)
# speedup vs baseline: 1.0060x; 1.0060x over previous
; __device__ __forceinline__ void finishSM(f32x16& p0, f32x16& p1, float alpha, float& l_reg, bf16x8& pa0, bf16x8& pa1, bf16x8& pa2, bf16x8& pa3) {
;     for (int r = 0; r < 16; ++r) p1[r] = __builtin_amdgcn_exp2f(p1[r]);
;     float ps = 0; for (int r = 0; r < 16; ++r) ps += p0[r]; for (int r = 0; r < 16; ++r) ps += p1[r];
;     { auto rr = __builtin_amdgcn_permlane32_swap(__float_as_uint(ps), __float_as_uint(ps), false, false);
;       ps = __uint_as_float(rr[0]) + __uint_as_float(rr[1]); }
;     l_reg = l_reg * alpha + ps;
;     ...
;     PK4(p0, 0, pa0); PK4(p0, 8, pa1); PK4(p1, 0, pa2); PK4(p1, 8, pa3);
.LBB0_89:
	ds_read_b128 v[66:69], v169 offset:49152
	ds_read_b128 v[70:73], v169 offset:57344
	ds_read_b128 v[100:103], v193 offset:49152
	s_waitcnt vmcnt(2)
	ds_read_b128 v[136:139], v193 offset:57344
	v_add_f32_e32 v148, 0, v231
	v_add_f32_e32 v148, v233, v148
	s_waitcnt lgkmcnt(3)
	v_mfma_f32_32x32x16_bf16 v[82:97], v[66:69], v[132:135], 0
	v_add_f32_e32 v148, v229, v148
	v_add_f32_e32 v148, v232, v148
	v_add_f32_e32 v148, v228, v148
	v_add_f32_e32 v148, v230, v148
	v_add_f32_e32 v148, v226, v148
	v_add_f32_e32 v148, v227, v148
	v_add_f32_e32 v148, v223, v148
	s_waitcnt lgkmcnt(2)
	v_mfma_f32_32x32x16_bf16 v[66:81], v[70:73], v[132:135], 0
	v_add_f32_e32 v148, v225, v148
	v_add_f32_e32 v148, v209, v148
	v_add_f32_e32 v148, v224, v148
	v_add_f32_e32 v148, v206, v148
	v_add_f32_e32 v148, v208, v148
	v_add_f32_e32 v148, v205, v148
	v_add_f32_e32 v148, v207, v148
	s_waitcnt lgkmcnt(1)
	v_mfma_f32_32x32x16_bf16 v[82:97], v[100:103], v[128:131], v[82:97]
	s_waitcnt vmcnt(1)
	v_exp_f32_e32 v140, v152
	v_exp_f32_e32 v141, v153
	v_exp_f32_e32 v142, v180
	v_exp_f32_e32 v143, v181
	s_waitcnt vmcnt(0)
	v_exp_f32_e32 v144, v160
	v_exp_f32_e32 v145, v161
	v_exp_f32_e32 v146, v154
	s_waitcnt lgkmcnt(0)
	v_mfma_f32_32x32x16_bf16 v[66:81], v[136:139], v[128:131], v[66:81]
	ds_read_b128 v[100:103], v194 offset:49152
	ds_read_b128 v[136:139], v194 offset:57344
	v_exp_f32_e32 v147, v155
	s_waitcnt lgkmcnt(1)
	v_mfma_f32_32x32x16_bf16 v[82:97], v[100:103], v[124:127], v[82:97]
	s_waitcnt lgkmcnt(0)
	v_mfma_f32_32x32x16_bf16 v[66:81], v[136:139], v[124:127], v[66:81]
	ds_read_b128 v[100:103], v195 offset:49152
	ds_read_b128 v[136:139], v195 offset:57344
	s_waitcnt lgkmcnt(1)
	v_mfma_f32_32x32x16_bf16 v[82:97], v[100:103], v[120:123], v[82:97]
	s_waitcnt lgkmcnt(0)
	v_mfma_f32_32x32x16_bf16 v[66:81], v[136:139], v[120:123], v[66:81]
	ds_read_b128 v[100:103], v169 offset:49280
	ds_read_b128 v[136:139], v169 offset:57472
	s_waitcnt lgkmcnt(1)
	v_mfma_f32_32x32x16_bf16 v[82:97], v[100:103], v[116:119], v[82:97]
	s_waitcnt lgkmcnt(0)
	v_mfma_f32_32x32x16_bf16 v[66:81], v[136:139], v[116:119], v[66:81]
	ds_read_b128 v[100:103], v193 offset:49280
	ds_read_b128 v[136:139], v193 offset:57472
	s_waitcnt lgkmcnt(1)
	v_mfma_f32_32x32x16_bf16 v[82:97], v[100:103], v[112:115], v[82:97]
	s_waitcnt lgkmcnt(0)
	v_mfma_f32_32x32x16_bf16 v[66:81], v[136:139], v[112:115], v[66:81]
	ds_read_b128 v[100:103], v194 offset:49280
	ds_read_b128 v[136:139], v194 offset:57472
	s_waitcnt lgkmcnt(1)
	v_mfma_f32_32x32x16_bf16 v[82:97], v[100:103], v[108:111], v[82:97]
	s_waitcnt lgkmcnt(0)
	v_mfma_f32_32x32x16_bf16 v[66:81], v[136:139], v[108:111], v[66:81]
	ds_read_b128 v[100:103], v195 offset:49280
	ds_read_b128 v[136:139], v195 offset:57472
	s_waitcnt lgkmcnt(1)
	v_mfma_f32_32x32x16_bf16 v[82:97], v[100:103], v[104:107], v[82:97]
	v_exp_f32_e32 v100, v178
	v_exp_f32_e32 v101, v179
	v_exp_f32_e32 v102, v162
	v_exp_f32_e32 v103, v163
	v_add_f32_e32 v148, v100, v148
	v_add_f32_e32 v148, v101, v148
	v_add_f32_e32 v148, v102, v148
	s_waitcnt lgkmcnt(0)
	v_mfma_f32_32x32x16_bf16 v[66:81], v[136:139], v[104:107], v[66:81]
	v_exp_f32_e32 v136, v158
	v_exp_f32_e32 v137, v159
	v_exp_f32_e32 v138, v156
	v_exp_f32_e32 v139, v157
	v_add_f32_e32 v148, v103, v148
	v_add_f32_e32 v148, v136, v148
	v_add_f32_e32 v148, v137, v148
	v_add_f32_e32 v148, v138, v148
	v_add_f32_e32 v148, v139, v148
	v_add_f32_e32 v148, v140, v148
	v_add_f32_e32 v148, v141, v148
	v_add_f32_e32 v148, v142, v148
	v_add_f32_e32 v148, v143, v148
	v_add_f32_e32 v148, v144, v148
	v_add_f32_e32 v148, v145, v148
	v_add_f32_e32 v148, v146, v148
	v_add_f32_e32 v199, v147, v148
	v_mov_b32_e32 v200, v199
	s_nop 1
	v_permlane32_swap_b32_e32 v199, v200
	v_cvt_pk_bf16_f32 v148, v231, v233
	v_cvt_pk_bf16_f32 v149, v229, v232
	v_cvt_pk_bf16_f32 v150, v228, v230
	v_cvt_pk_bf16_f32 v151, v226, v227
	v_cvt_pk_bf16_f32 v152, v223, v225
	v_cvt_pk_bf16_f32 v153, v209, v224
	v_cvt_pk_bf16_f32 v154, v206, v208
	v_cvt_pk_bf16_f32 v155, v205, v207
	v_cvt_pk_bf16_f32 v156, v100, v101
	v_cvt_pk_bf16_f32 v157, v102, v103
	v_cvt_pk_bf16_f32 v158, v136, v137
	v_cvt_pk_bf16_f32 v159, v138, v139
	v_cvt_pk_bf16_f32 v160, v140, v141
	v_cvt_pk_bf16_f32 v161, v142, v143
	v_cvt_pk_bf16_f32 v162, v144, v145
	v_cvt_pk_bf16_f32 v163, v146, v147
	s_nop 0
	v_permlane32_swap_b32_e32 v148, v150
	v_permlane32_swap_b32_e32 v149, v151
	v_permlane32_swap_b32_e32 v152, v154
	v_permlane32_swap_b32_e32 v153, v155
	v_permlane32_swap_b32_e32 v156, v158
	v_permlane32_swap_b32_e32 v157, v159
	v_permlane32_swap_b32_e32 v160, v162
	v_permlane32_swap_b32_e32 v161, v163
	v_add_u32_e32 v178, s7, v166
	v_add_u32_e32 v100, 1, v178
	v_add_u32_e32 v102, 33, v178
	v_ashrrev_i32_e32 v101, 31, v100
	v_ashrrev_i32_e32 v103, 31, v102
	v_lshlrev_b64 v[140:141], 8, v[100:101]
	v_lshlrev_b64 v[142:143], 8, v[102:103]
	v_lshl_add_u64 v[100:101], v[170:171], 0, v[140:141]
	v_lshl_add_u64 v[136:137], v[170:171], 0, v[142:143]
	v_lshl_add_u64 v[140:141], v[176:177], 0, v[140:141]
	v_lshl_add_u64 v[144:145], v[176:177], 0, v[142:143]
	global_load_dwordx4 v[100:103], v[100:101], off
	s_nop 0
	global_load_dwordx4 v[136:139], v[136:137], off
	s_nop 0
	global_load_dwordx4 v[140:143], v[140:141], off
	s_nop 0
	global_load_dwordx4 v[144:147], v[144:145], off
	s_cmp_le_i32 s7, s6
	s_cbranch_scc0 .Lmy_hs1_slow
; __device__ __forceinline__ void partialSM(f32x16& p0, f32x16& p1, float& m_reg, float& mn, float& alpha, bool rs) {
;     float pmax = p0[0]; for (int r = 1; r < 16; ++r) pmax = fmaxf(pmax, p0[r]); for (int r = 0; r < 16; ++r) pmax = fmaxf(pmax, p1[r]);
;     if (!rs) pmax = -__builtin_inff();
;     { auto rr = __builtin_amdgcn_permlane32_swap(__float_as_uint(pmax), __float_as_uint(pmax), false, false);
;       pmax = fmaxf(__uint_as_float(rr[0]), __uint_as_float(rr[1])); }
;     constexpr float C2 = 1.4426950408889634f * SCALE;
;     if (__builtin_expect(__all((pmax - m_reg) * SCALE <= THR), 1)) { mn = m_reg; alpha = 1.f; }
;     else { mn = fmaxf(m_reg, pmax); alpha = __builtin_amdgcn_exp2f((m_reg - mn) * C2); m_reg = mn; }
;     const float mnL = rs ? -mn * C2 : -__builtin_inff();
;     for (int r = 0; r < 16; ++r) p0[r] = fmaf(p0[r], C2, mnL); for (int r = 0; r < 16; ++r) p1[r] = fmaf(p1[r], C2, mnL);
;     for (int r = 0; r < 16; ++r) p0[r] = __builtin_amdgcn_exp2f(p0[r]);
; template <int VB>
; __device__ __forceinline__ void pv_tile(f32x16* o, int vb0, bf16x8 pa0, bf16x8 pa1, bf16x8 pa2, bf16x8 pa3) {
;     ...
;     PV_D0(0); PV_D0(1); PV_D0(2); PV_D0(3);
;     ...
; }
	ds_read_b64_tr_b16 v[172:173], v185 offset:0
	ds_read_b64_tr_b16 v[174:175], v185 offset:0x800
	ds_read_b64_tr_b16 v[202:203], v185 offset:0x1000
	ds_read_b64_tr_b16 v[204:205], v185 offset:0x1800
	ds_read_b64_tr_b16 v[206:207], v185 offset:0x2000
	ds_read_b64_tr_b16 v[208:209], v185 offset:0x2800
	ds_read_b64_tr_b16 v[224:225], v185 offset:0x3000
	ds_read_b64_tr_b16 v[226:227], v185 offset:0x3800
	s_waitcnt lgkmcnt(0)
	s_nop 0
	v_mfma_f32_32x32x16_bf16 v[50:65], v[148:151], v[172:175], v[50:65]
	ds_read_b64_tr_b16 v[172:173], v185 offset:0x200
	ds_read_b64_tr_b16 v[174:175], v185 offset:0xa00
	v_mfma_f32_32x32x16_bf16 v[50:65], v[152:155], v[202:205], v[50:65]
	s_add_i32 s0, s3, -2
	s_lshr_b32 s8, s0, 2
	s_cmp_ge_i32 s8, s44
	s_cselect_b64 s[0:1], -1, 0
	s_lshl_b32 s8, 1, s8
	v_and_b32_e32 v250, s8, v165
	ds_read_b64_tr_b16 v[202:203], v185 offset:0x1200
	ds_read_b64_tr_b16 v[204:205], v185 offset:0x1a00
	v_mfma_f32_32x32x16_bf16 v[50:65], v[156:159], v[206:209], v[50:65]
	v_cmp_ne_u32_e32 vcc, 0, v250
	v_max_f32_e32 v250, v83, v83
	v_max_f32_e32 v251, v82, v82
	v_max_f32_e32 v250, v251, v250
	v_max3_f32 v250, v250, v84, v85
	ds_read_b64_tr_b16 v[206:207], v185 offset:0x2200
	ds_read_b64_tr_b16 v[208:209], v185 offset:0x2a00
	v_mfma_f32_32x32x16_bf16 v[50:65], v[160:163], v[224:227], v[50:65]
	v_max3_f32 v250, v250, v86, v87
	v_max3_f32 v250, v250, v88, v89
	v_max3_f32 v250, v250, v90, v91
	v_max3_f32 v250, v250, v92, v93
	v_max3_f32 v250, v250, v94, v95
	ds_read_b64_tr_b16 v[224:225], v185 offset:0x3200
	ds_read_b64_tr_b16 v[226:227], v185 offset:0x3a00
	s_waitcnt lgkmcnt(0)
	v_mfma_f32_32x32x16_bf16 v[34:49], v[148:151], v[172:175], v[34:49]
	v_max3_f32 v250, v250, v96, v97
	v_max3_f32 v250, v250, v66, v67
	v_max3_f32 v250, v250, v68, v69
	v_max3_f32 v250, v250, v70, v71
	v_max3_f32 v250, v250, v72, v73
	ds_read_b64_tr_b16 v[172:173], v185 offset:0x400
	ds_read_b64_tr_b16 v[174:175], v185 offset:0xc00
	v_mfma_f32_32x32x16_bf16 v[34:49], v[152:155], v[202:205], v[34:49]
	v_max3_f32 v250, v250, v74, v75
	v_max3_f32 v250, v250, v76, v77
	v_max3_f32 v250, v250, v78, v79
	s_or_b64 s[40:41], s[0:1], vcc
	v_max3_f32 v250, v250, v80, v81
	ds_read_b64_tr_b16 v[202:203], v185 offset:0x1400
	ds_read_b64_tr_b16 v[204:205], v185 offset:0x1c00
	v_mfma_f32_32x32x16_bf16 v[34:49], v[156:159], v[206:209], v[34:49]
	v_cndmask_b32_e64 v250, v220, v250, s[40:41]
	v_mov_b32_e32 v251, v250
	s_nop 1
	v_permlane32_swap_b32_e32 v250, v251
	v_max_f32_e32 v251, v251, v251
	v_max_f32_e32 v250, v250, v250
	v_max_f32_e32 v250, v250, v251
	ds_read_b64_tr_b16 v[206:207], v185 offset:0x2400
	ds_read_b64_tr_b16 v[208:209], v185 offset:0x2c00
	v_mfma_f32_32x32x16_bf16 v[34:49], v[160:163], v[224:227], v[34:49]
	v_sub_f32_e32 v251, v250, v198
	v_mul_f32_e32 v251, 0x3db504f3, v251
	v_cmp_ge_f32_e32 vcc, s91, v251
	v_max_f32_e32 v251, v198, v198
	v_max_f32_e32 v250, v251, v250
	ds_read_b64_tr_b16 v[224:225], v185 offset:0x3400
	ds_read_b64_tr_b16 v[226:227], v185 offset:0x3c00
	s_waitcnt lgkmcnt(0)
	v_mfma_f32_32x32x16_bf16 v[18:33], v[148:151], v[172:175], v[18:33]
	v_sub_f32_e32 v251, v198, v250
	v_mul_f32_e32 v251, 0x3e0293ee, v251
	v_exp_f32_e32 v251, v251
	s_cmp_eq_u64 vcc, exec
	s_cselect_b64 s[42:43], -1, 0
	v_cndmask_b32_e64 v179, v250, v198, s[42:43]
	ds_read_b64_tr_b16 v[172:173], v185 offset:0x600
	ds_read_b64_tr_b16 v[174:175], v185 offset:0xe00
	v_mfma_f32_32x32x16_bf16 v[18:33], v[152:155], v[202:205], v[18:33]
	v_mul_f32_e32 v222, 0xbe0293ee, v179
	v_cndmask_b32_e64 v180, v220, v222, s[40:41]
	v_fmamk_f32 v82, v82, 0x3e0293ee, v180
	v_fmamk_f32 v83, v83, 0x3e0293ee, v180
	v_fmamk_f32 v84, v84, 0x3e0293ee, v180
	ds_read_b64_tr_b16 v[202:203], v185 offset:0x1600
	ds_read_b64_tr_b16 v[204:205], v185 offset:0x1e00
	v_mfma_f32_32x32x16_bf16 v[18:33], v[156:159], v[206:209], v[18:33]
	v_fmamk_f32 v85, v85, 0x3e0293ee, v180
	v_fmamk_f32 v86, v86, 0x3e0293ee, v180
	v_fmamk_f32 v87, v87, 0x3e0293ee, v180
	v_fmamk_f32 v88, v88, 0x3e0293ee, v180
	v_fmamk_f32 v89, v89, 0x3e0293ee, v180
	ds_read_b64_tr_b16 v[206:207], v185 offset:0x2600
	ds_read_b64_tr_b16 v[208:209], v185 offset:0x2e00
	v_mfma_f32_32x32x16_bf16 v[18:33], v[160:163], v[224:227], v[18:33]
	v_fmamk_f32 v90, v90, 0x3e0293ee, v180
	v_fmamk_f32 v91, v91, 0x3e0293ee, v180
	v_fmamk_f32 v92, v92, 0x3e0293ee, v180
	v_fmamk_f32 v93, v93, 0x3e0293ee, v180
	v_fmamk_f32 v94, v94, 0x3e0293ee, v180
	ds_read_b64_tr_b16 v[224:225], v185 offset:0x3600
	ds_read_b64_tr_b16 v[226:227], v185 offset:0x3e00
	s_waitcnt lgkmcnt(0)
	v_mfma_f32_32x32x16_bf16 v[2:17], v[148:151], v[172:175], v[2:17]
	v_fmamk_f32 v95, v95, 0x3e0293ee, v180
	v_fmamk_f32 v96, v96, 0x3e0293ee, v180
	v_fmamk_f32 v97, v97, 0x3e0293ee, v180
	v_exp_f32_e32 v234, v82
	v_exp_f32_e32 v249, v83
	v_mfma_f32_32x32x16_bf16 v[2:17], v[152:155], v[202:205], v[2:17]
	v_exp_f32_e32 v235, v84
	v_exp_f32_e32 v248, v85
	v_exp_f32_e32 v236, v86
	v_exp_f32_e32 v247, v87
	v_exp_f32_e32 v237, v88
	v_mfma_f32_32x32x16_bf16 v[2:17], v[156:159], v[206:209], v[2:17]
	v_exp_f32_e32 v246, v89
	v_exp_f32_e32 v238, v90
	v_exp_f32_e32 v245, v91
	v_exp_f32_e32 v239, v92
	v_exp_f32_e32 v244, v93
	v_mfma_f32_32x32x16_bf16 v[2:17], v[160:163], v[224:227], v[2:17]
	v_exp_f32_e32 v240, v94
	v_exp_f32_e32 v243, v95
	v_exp_f32_e32 v241, v96
	v_exp_f32_e32 v242, v97
	v_mov_b32_e32 v149, v251
	s_mov_b32 s100, 1
	s_branch .Lmy_hs1_b1
; __device__ __forceinline__ void mask_tile(f32x16& p0, f32x16& p1, int dq, unsigned W) {
;     const float NEG = -__builtin_inff();
; #pragma unroll
;     for (int r = 0; r < 16; ++r) {
;         const int c = (r & 3) + 8 * (r >> 2);
;         if ((unsigned)(dq - c) >= W) p0[r] = NEG;
;         if ((unsigned)(dq - c - 32) >= W) p1[r] = NEG;
;     }
; }
; template <int VB>
; __device__ __forceinline__ void pv_tile(f32x16* o, int vb0, bf16x8 pa0, bf16x8 pa1, bf16x8 pa2, bf16x8 pa3) {
;     ...
;     PV_D0(0); PV_D0(1); PV_D0(2); PV_D0(3);
;     ...
; }
.Lmy_hs1_slow:
	ds_read_b64_tr_b16 v[172:173], v185 offset:0
	ds_read_b64_tr_b16 v[174:175], v185 offset:0x800
	ds_read_b64_tr_b16 v[202:203], v185 offset:0x1000
	ds_read_b64_tr_b16 v[204:205], v185 offset:0x1800
	ds_read_b64_tr_b16 v[206:207], v185 offset:0x2000
	ds_read_b64_tr_b16 v[208:209], v185 offset:0x2800
	ds_read_b64_tr_b16 v[224:225], v185 offset:0x3000
	ds_read_b64_tr_b16 v[226:227], v185 offset:0x3800
	s_waitcnt lgkmcnt(0)
	s_nop 0
	v_mfma_f32_32x32x16_bf16 v[50:65], v[148:151], v[172:175], v[50:65]
	ds_read_b64_tr_b16 v[172:173], v185 offset:0x200
	ds_read_b64_tr_b16 v[174:175], v185 offset:0xa00
	v_mfma_f32_32x32x16_bf16 v[50:65], v[152:155], v[202:205], v[50:65]
	ds_read_b64_tr_b16 v[202:203], v185 offset:0x1200
	ds_read_b64_tr_b16 v[204:205], v185 offset:0x1a00
	v_mfma_f32_32x32x16_bf16 v[50:65], v[156:159], v[206:209], v[50:65]
	ds_read_b64_tr_b16 v[206:207], v185 offset:0x2200
	ds_read_b64_tr_b16 v[208:209], v185 offset:0x2a00
	v_mfma_f32_32x32x16_bf16 v[50:65], v[160:163], v[224:227], v[50:65]
	ds_read_b64_tr_b16 v[224:225], v185 offset:0x3200
	ds_read_b64_tr_b16 v[226:227], v185 offset:0x3a00
	s_waitcnt lgkmcnt(0)
	v_mfma_f32_32x32x16_bf16 v[34:49], v[148:151], v[172:175], v[34:49]
	ds_read_b64_tr_b16 v[172:173], v185 offset:0x400
	ds_read_b64_tr_b16 v[174:175], v185 offset:0xc00
	v_mfma_f32_32x32x16_bf16 v[34:49], v[152:155], v[202:205], v[34:49]
	ds_read_b64_tr_b16 v[202:203], v185 offset:0x1400
	ds_read_b64_tr_b16 v[204:205], v185 offset:0x1c00
	v_mfma_f32_32x32x16_bf16 v[34:49], v[156:159], v[206:209], v[34:49]
	ds_read_b64_tr_b16 v[206:207], v185 offset:0x2400
	ds_read_b64_tr_b16 v[208:209], v185 offset:0x2c00
	v_mfma_f32_32x32x16_bf16 v[34:49], v[160:163], v[224:227], v[34:49]
	ds_read_b64_tr_b16 v[224:225], v185 offset:0x3400
	ds_read_b64_tr_b16 v[226:227], v185 offset:0x3c00
	s_waitcnt lgkmcnt(0)
	v_mfma_f32_32x32x16_bf16 v[18:33], v[148:151], v[172:175], v[18:33]
	ds_read_b64_tr_b16 v[172:173], v185 offset:0x600
	ds_read_b64_tr_b16 v[174:175], v185 offset:0xe00
	v_mfma_f32_32x32x16_bf16 v[18:33], v[152:155], v[202:205], v[18:33]
	ds_read_b64_tr_b16 v[202:203], v185 offset:0x1600
	ds_read_b64_tr_b16 v[204:205], v185 offset:0x1e00
	v_mfma_f32_32x32x16_bf16 v[18:33], v[156:159], v[206:209], v[18:33]
	ds_read_b64_tr_b16 v[206:207], v185 offset:0x2600
	ds_read_b64_tr_b16 v[208:209], v185 offset:0x2e00
	v_mfma_f32_32x32x16_bf16 v[18:33], v[160:163], v[224:227], v[18:33]
	ds_read_b64_tr_b16 v[224:225], v185 offset:0x3600
	ds_read_b64_tr_b16 v[226:227], v185 offset:0x3e00
	s_waitcnt lgkmcnt(0)
	v_mfma_f32_32x32x16_bf16 v[2:17], v[148:151], v[172:175], v[2:17]
	s_cmp_le_i32 s7, s6
	v_mfma_f32_32x32x16_bf16 v[2:17], v[152:155], v[202:205], v[2:17]
	v_mfma_f32_32x32x16_bf16 v[2:17], v[156:159], v[206:209], v[2:17]
	v_mfma_f32_32x32x16_bf16 v[2:17], v[160:163], v[224:227], v[2:17]
	v_add_u32_e32 v148, 0x4000007b, v197
	v_cmp_gt_u32_e32 vcc, 2.0, v148
	v_add_u32_e32 v148, 0x5b, v197
	s_nop 0
	v_cndmask_b32_e32 v82, v220, v82, vcc
	v_cmp_lt_u32_e32 vcc, s33, v148
	v_add_u32_e32 v148, 0x7a, v197
	s_nop 0
	v_cndmask_b32_e32 v66, v220, v66, vcc
	v_cmp_lt_u32_e32 vcc, s33, v148
	v_add_u32_e32 v148, 0x5a, v197
	s_nop 0
	v_cndmask_b32_e32 v83, v220, v83, vcc
	v_cmp_lt_u32_e32 vcc, s33, v148
	v_add_u32_e32 v148, 0x79, v197
	s_nop 0
	v_cndmask_b32_e32 v67, v220, v67, vcc
	v_cmp_lt_u32_e32 vcc, s33, v148
	v_add_u32_e32 v148, 0x59, v197
	s_nop 0
	v_cndmask_b32_e32 v84, v220, v84, vcc
	v_cmp_lt_u32_e32 vcc, s33, v148
	v_add_u32_e32 v148, 0x78, v197
	s_nop 0
	v_cndmask_b32_e32 v68, v220, v68, vcc
	v_cmp_lt_u32_e32 vcc, s33, v148
	v_add_u32_e32 v148, 0x58, v197
	s_nop 0
	v_cndmask_b32_e32 v85, v220, v85, vcc
	v_cmp_lt_u32_e32 vcc, s33, v148
	v_add_u32_e32 v148, 0x73, v197
	s_nop 0
	v_cndmask_b32_e32 v69, v220, v69, vcc
	v_cmp_lt_u32_e32 vcc, s33, v148
	v_add_u32_e32 v148, 0x53, v197
	s_nop 0
	v_cndmask_b32_e32 v86, v220, v86, vcc
	v_cmp_lt_u32_e32 vcc, s33, v148
	v_add_u32_e32 v148, 0x72, v197
	s_nop 0
	v_cndmask_b32_e32 v70, v220, v70, vcc
	v_cmp_lt_u32_e32 vcc, s33, v148
	v_add_u32_e32 v148, 0x52, v197
	s_nop 0
	v_cndmask_b32_e32 v87, v220, v87, vcc
	v_cmp_lt_u32_e32 vcc, s33, v148
	v_add_u32_e32 v148, 0x71, v197
	s_nop 0
	v_cndmask_b32_e32 v71, v220, v71, vcc
	v_cmp_lt_u32_e32 vcc, s33, v148
	v_add_u32_e32 v148, 0x51, v197
	s_nop 0
	v_cndmask_b32_e32 v88, v220, v88, vcc
	v_cmp_lt_u32_e32 vcc, s33, v148
	v_add_u32_e32 v148, 0x70, v197
	s_nop 0
	v_cndmask_b32_e32 v72, v220, v72, vcc
	v_cmp_lt_u32_e32 vcc, s33, v148
	v_add_u32_e32 v148, 0x50, v197
	s_nop 0
	v_cndmask_b32_e32 v89, v220, v89, vcc
	v_cmp_lt_u32_e32 vcc, s33, v148
	v_add_u32_e32 v148, 0x6b, v197
	s_nop 0
	v_cndmask_b32_e32 v73, v220, v73, vcc
	v_cmp_lt_u32_e32 vcc, s33, v148
	v_add_u32_e32 v148, 0x4b, v197
	s_nop 0
	v_cndmask_b32_e32 v90, v220, v90, vcc
	v_cmp_lt_u32_e32 vcc, s33, v148
	v_add_u32_e32 v148, 0x6a, v197
	s_nop 0
	v_cndmask_b32_e32 v74, v220, v74, vcc
	v_cmp_lt_u32_e32 vcc, s33, v148
	v_add_u32_e32 v148, 0x4a, v197
	s_nop 0
	v_cndmask_b32_e32 v91, v220, v91, vcc
	v_cmp_lt_u32_e32 vcc, s33, v148
	v_add_u32_e32 v148, 0x69, v197
	s_nop 0
	v_cndmask_b32_e32 v75, v220, v75, vcc
	v_cmp_lt_u32_e32 vcc, s33, v148
	v_add_u32_e32 v148, 0x49, v197
	s_nop 0
	v_cndmask_b32_e32 v92, v220, v92, vcc
	v_cmp_lt_u32_e32 vcc, s33, v148
	v_add_u32_e32 v148, 0x68, v197
	s_nop 0
	v_cndmask_b32_e32 v76, v220, v76, vcc
	v_cmp_lt_u32_e32 vcc, s33, v148
	v_add_u32_e32 v148, 0x48, v197
	s_nop 0
	v_cndmask_b32_e32 v93, v220, v93, vcc
	v_cmp_lt_u32_e32 vcc, s33, v148
	v_add_u32_e32 v148, 0x63, v197
	s_nop 0
	v_cndmask_b32_e32 v77, v220, v77, vcc
	v_cmp_lt_u32_e32 vcc, s33, v148
	v_add_u32_e32 v148, 0x43, v197
	s_nop 0
	v_cndmask_b32_e32 v94, v220, v94, vcc
	v_cmp_lt_u32_e32 vcc, s33, v148
	v_add_u32_e32 v148, 0x62, v197
	s_nop 0
	v_cndmask_b32_e32 v78, v220, v78, vcc
	v_cmp_lt_u32_e32 vcc, s33, v148
	v_add_u32_e32 v148, 0x42, v197
	s_nop 0
	v_cndmask_b32_e32 v95, v220, v95, vcc
	v_cmp_lt_u32_e32 vcc, s33, v148
	v_add_u32_e32 v148, 0x61, v197
	s_nop 0
	v_cndmask_b32_e32 v79, v220, v79, vcc
	v_cmp_lt_u32_e32 vcc, s33, v148
	v_add_u32_e32 v148, 0x41, v197
	s_nop 0
	v_cndmask_b32_e32 v96, v220, v96, vcc
	v_cmp_lt_u32_e32 vcc, s33, v148
	v_add_u32_e32 v148, 0x60, v197
	s_nop 0
	v_cndmask_b32_e32 v80, v220, v80, vcc
	v_cmp_lt_u32_e32 vcc, s33, v148
	v_add_u32_e32 v148, 64, v197
	s_nop 0
	v_cndmask_b32_e32 v97, v220, v97, vcc
	v_cmp_lt_u32_e32 vcc, s33, v148
	s_nop 1
	v_cndmask_b32_e32 v81, v220, v81, vcc
; __device__ __forceinline__ void partialSM(f32x16& p0, f32x16& p1, float& m_reg, float& mn, float& alpha, bool rs) {
;     float pmax = p0[0]; for (int r = 1; r < 16; ++r) pmax = fmaxf(pmax, p0[r]); for (int r = 0; r < 16; ++r) pmax = fmaxf(pmax, p1[r]);
;     if (!rs) pmax = -__builtin_inff();
;     { auto rr = __builtin_amdgcn_permlane32_swap(__float_as_uint(pmax), __float_as_uint(pmax), false, false);
;       pmax = fmaxf(__uint_as_float(rr[0]), __uint_as_float(rr[1])); }
;     constexpr float C2 = 1.4426950408889634f * SCALE;
;     if (__builtin_expect(__all((pmax - m_reg) * SCALE <= THR), 1)) { mn = m_reg; alpha = 1.f; }
;     else { mn = fmaxf(m_reg, pmax); alpha = __builtin_amdgcn_exp2f((m_reg - mn) * C2); m_reg = mn; }
;     const float mnL = rs ? -mn * C2 : -__builtin_inff();
;     for (int r = 0; r < 16; ++r) p0[r] = fmaf(p0[r], C2, mnL); for (int r = 0; r < 16; ++r) p1[r] = fmaf(p1[r], C2, mnL);
;     for (int r = 0; r < 16; ++r) p0[r] = __builtin_amdgcn_exp2f(p0[r]);
.LBB0_91:
	s_add_i32 s0, s3, -2
	s_lshr_b32 s8, s0, 2
	s_cmp_ge_i32 s8, s44
	s_cselect_b64 s[0:1], -1, 0
	s_lshl_b32 s8, 1, s8
	v_and_b32_e32 v148, s8, v165
	v_cmp_ne_u32_e32 vcc, 0, v148
	v_max_f32_e32 v148, v83, v83
	v_max_f32_e32 v149, v82, v82
	v_max_f32_e32 v148, v149, v148
	v_max3_f32 v148, v148, v84, v85
	v_max3_f32 v148, v148, v86, v87
	v_max3_f32 v148, v148, v88, v89
	v_max3_f32 v148, v148, v90, v91
	v_max3_f32 v148, v148, v92, v93
	v_max3_f32 v148, v148, v94, v95
	v_max3_f32 v148, v148, v96, v97
	v_max3_f32 v148, v148, v66, v67
	v_max3_f32 v148, v148, v68, v69
	v_max3_f32 v148, v148, v70, v71
	v_max3_f32 v148, v148, v72, v73
	v_max3_f32 v148, v148, v74, v75
	v_max3_f32 v148, v148, v76, v77
	v_max3_f32 v148, v148, v78, v79
	s_or_b64 s[40:41], s[0:1], vcc
	v_max3_f32 v148, v148, v80, v81
	v_cndmask_b32_e64 v148, v220, v148, s[40:41]
	v_mov_b32_e32 v149, v148
	s_nop 1
	v_permlane32_swap_b32_e32 v148, v149
	v_max_f32_e32 v149, v149, v149
	v_max_f32_e32 v148, v148, v148
	v_max_f32_e32 v148, v148, v149
	v_sub_f32_e32 v149, v148, v198
	v_mul_f32_e32 v149, 0x3db504f3, v149
	v_cmp_ge_f32_e32 vcc, s91, v149
	v_max_f32_e32 v149, v198, v198
	v_max_f32_e32 v148, v149, v148
	v_sub_f32_e32 v149, v198, v148
	v_mul_f32_e32 v149, 0x3e0293ee, v149
	v_exp_f32_e32 v149, v149
	s_cmp_eq_u64 vcc, exec
	s_cselect_b64 s[42:43], -1, 0
	s_mov_b32 s100, 0
.Lmy_hs1_b1:
	s_barrier
	s_waitcnt vmcnt(0)
	v_cndmask_b32_e64 v202, v149, 1.0, s[42:43]
	v_cmp_gt_f32_e32 vcc, 1.0, v202
	s_waitcnt vmcnt(3)
	ds_write_b128 v191, v[100:103]
	s_waitcnt vmcnt(2)
	ds_write_b128 v192, v[136:139]
	s_waitcnt vmcnt(1)
	ds_write_b128 v188, v[140:143] offset:32768
	s_waitcnt vmcnt(0)
	ds_write_b128 v188, v[144:147] offset:40960
	s_cbranch_vccz .LBB0_95
	s_and_saveexec_b64 s[0:1], s[38:39]
	ds_write_b32 v187, v202 offset:128
	s_or_b64 exec, exec, s[0:1]
	s_waitcnt lgkmcnt(0)
	ds_read_b128 v[150:153], v186 offset:224
	ds_read_b128 v[154:157], v186 offset:192
	ds_read_b128 v[158:161], v186 offset:160
	ds_read_b128 v[172:175], v186 offset:128
	s_waitcnt lgkmcnt(3)
	v_pk_mul_f32 v[64:65], v[64:65], v[152:153]
	s_waitcnt lgkmcnt(2)
	v_pk_mul_f32 v[60:61], v[60:61], v[156:157]
	s_waitcnt lgkmcnt(1)
	v_pk_mul_f32 v[56:57], v[56:57], v[160:161]
	s_waitcnt lgkmcnt(0)
	v_pk_mul_f32 v[52:53], v[52:53], v[174:175]
	v_pk_mul_f32 v[62:63], v[62:63], v[150:151]
	v_pk_mul_f32 v[58:59], v[58:59], v[154:155]
	v_pk_mul_f32 v[54:55], v[54:55], v[158:159]
	v_pk_mul_f32 v[50:51], v[50:51], v[172:173]
	v_pk_mul_f32 v[48:49], v[48:49], v[152:153]
	v_pk_mul_f32 v[44:45], v[44:45], v[156:157]
	v_pk_mul_f32 v[40:41], v[40:41], v[160:161]
	v_pk_mul_f32 v[36:37], v[36:37], v[174:175]
	v_pk_mul_f32 v[46:47], v[46:47], v[150:151]
	v_pk_mul_f32 v[42:43], v[42:43], v[154:155]
	v_pk_mul_f32 v[38:39], v[38:39], v[158:159]
	v_pk_mul_f32 v[34:35], v[34:35], v[172:173]
	v_pk_mul_f32 v[32:33], v[32:33], v[152:153]
	v_pk_mul_f32 v[28:29], v[28:29], v[156:157]
	v_pk_mul_f32 v[24:25], v[24:25], v[160:161]
	v_pk_mul_f32 v[20:21], v[20:21], v[174:175]
	v_pk_mul_f32 v[30:31], v[30:31], v[150:151]
	v_pk_mul_f32 v[26:27], v[26:27], v[154:155]
	v_pk_mul_f32 v[22:23], v[22:23], v[158:159]
	v_pk_mul_f32 v[18:19], v[18:19], v[172:173]
	v_pk_mul_f32 v[16:17], v[16:17], v[152:153]
	v_pk_mul_f32 v[12:13], v[12:13], v[156:157]
	v_pk_mul_f32 v[8:9], v[8:9], v[160:161]
	v_pk_mul_f32 v[4:5], v[4:5], v[174:175]
	v_pk_mul_f32 v[14:15], v[14:15], v[150:151]
	v_pk_mul_f32 v[10:11], v[10:11], v[154:155]
	v_pk_mul_f32 v[6:7], v[6:7], v[158:159]
	v_pk_mul_f32 v[2:3], v[2:3], v[172:173]
.LBB0_95:
	s_cmp_eq_u32 s100, 1
	s_cbranch_scc1 .Lmy_hs1_p1
	v_cndmask_b32_e64 v179, v148, v198, s[42:43]
	v_mul_f32_e32 v148, 0xbe0293ee, v179
	v_cndmask_b32_e64 v180, v220, v148, s[40:41]
	v_fmamk_f32 v82, v82, 0x3e0293ee, v180
	v_fmamk_f32 v83, v83, 0x3e0293ee, v180
	v_fmamk_f32 v84, v84, 0x3e0293ee, v180
	v_fmamk_f32 v85, v85, 0x3e0293ee, v180
	v_fmamk_f32 v86, v86, 0x3e0293ee, v180
	v_fmamk_f32 v87, v87, 0x3e0293ee, v180
	v_fmamk_f32 v88, v88, 0x3e0293ee, v180
	v_fmamk_f32 v89, v89, 0x3e0293ee, v180
	v_fmamk_f32 v90, v90, 0x3e0293ee, v180
	v_fmamk_f32 v91, v91, 0x3e0293ee, v180
	v_fmamk_f32 v92, v92, 0x3e0293ee, v180
	v_fmamk_f32 v93, v93, 0x3e0293ee, v180
	v_fmamk_f32 v94, v94, 0x3e0293ee, v180
	v_fmamk_f32 v95, v95, 0x3e0293ee, v180
	v_fmamk_f32 v96, v96, 0x3e0293ee, v180
	v_fmamk_f32 v97, v97, 0x3e0293ee, v180
	v_exp_f32_e32 v234, v82
	v_exp_f32_e32 v249, v83
	v_exp_f32_e32 v235, v84
	v_exp_f32_e32 v248, v85
	v_exp_f32_e32 v236, v86
	v_exp_f32_e32 v247, v87
	v_exp_f32_e32 v237, v88
	v_exp_f32_e32 v246, v89
	v_exp_f32_e32 v238, v90
	v_exp_f32_e32 v245, v91
	v_exp_f32_e32 v239, v92
	v_exp_f32_e32 v244, v93
	v_exp_f32_e32 v240, v94
	v_exp_f32_e32 v243, v95
	v_exp_f32_e32 v241, v96
	v_exp_f32_e32 v242, v97
; __device__ __forceinline__ void finishSM(f32x16& p0, f32x16& p1, float alpha, float& l_reg, bf16x8& pa0, bf16x8& pa1, bf16x8& pa2, bf16x8& pa3) {
;     for (int r = 0; r < 16; ++r) p1[r] = __builtin_amdgcn_exp2f(p1[r]);
;     float ps = 0; for (int r = 0; r < 16; ++r) ps += p0[r]; for (int r = 0; r < 16; ++r) ps += p1[r];
;     { auto rr = __builtin_amdgcn_permlane32_swap(__float_as_uint(ps), __float_as_uint(ps), false, false);
;       ps = __uint_as_float(rr[0]) + __uint_as_float(rr[1]); }
;     l_reg = l_reg * alpha + ps;
;     ...
;     PK4(p0, 0, pa0); PK4(p0, 8, pa1); PK4(p1, 0, pa2); PK4(p1, 8, pa3);
.Lmy_hs1_p1:
	v_fmamk_f32 v203, v73, 0x3e0293ee, v180
	v_fmamk_f32 v204, v74, 0x3e0293ee, v180
	v_fmamk_f32 v208, v66, 0x3e0293ee, v180
	v_fmamk_f32 v209, v67, 0x3e0293ee, v180
	v_fmamk_f32 v223, v68, 0x3e0293ee, v180
	v_fmamk_f32 v224, v69, 0x3e0293ee, v180
	v_fmamk_f32 v225, v70, 0x3e0293ee, v180
	v_fmamk_f32 v198, v71, 0x3e0293ee, v180
	v_fmamk_f32 v201, v72, 0x3e0293ee, v180
	v_fmamk_f32 v205, v75, 0x3e0293ee, v180
	v_fmamk_f32 v206, v76, 0x3e0293ee, v180
	v_fmamk_f32 v207, v77, 0x3e0293ee, v180
	v_fmamk_f32 v181, v78, 0x3e0293ee, v180
	v_fmamk_f32 v226, v79, 0x3e0293ee, v180
	v_fmamk_f32 v227, v80, 0x3e0293ee, v180
	v_fmac_f32_e32 v180, 0x3e0293ee, v81
	s_waitcnt lgkmcnt(0)
	s_barrier
	ds_read_b128 v[66:69], v169 offset:32768
	ds_read_b128 v[70:73], v169 offset:40960
	ds_read_b128 v[172:175], v193 offset:32768
	ds_read_b128 v[228:231], v193 offset:40960
	v_exp_f32_e32 v198, v198
	v_exp_f32_e32 v201, v201
	s_waitcnt lgkmcnt(3)
	v_mfma_f32_32x32x16_bf16 v[82:97], v[66:69], v[132:135], 0
	v_exp_f32_e32 v214, v204
	v_exp_f32_e32 v205, v205
	v_exp_f32_e32 v206, v206
	v_exp_f32_e32 v207, v207
	v_exp_f32_e32 v181, v181
	v_exp_f32_e32 v215, v226
	v_exp_f32_e32 v216, v227
	s_waitcnt lgkmcnt(2)
	v_mfma_f32_32x32x16_bf16 v[66:81], v[70:73], v[132:135], 0
	v_exp_f32_e32 v180, v180
	s_waitcnt lgkmcnt(1)
	v_mfma_f32_32x32x16_bf16 v[82:97], v[172:175], v[128:131], v[82:97]
	s_waitcnt lgkmcnt(0)
	v_mfma_f32_32x32x16_bf16 v[66:81], v[228:231], v[128:131], v[66:81]
	ds_read_b128 v[172:175], v194 offset:32768
	ds_read_b128 v[228:231], v194 offset:40960
	s_waitcnt lgkmcnt(1)
	v_mfma_f32_32x32x16_bf16 v[82:97], v[172:175], v[124:127], v[82:97]
	s_waitcnt lgkmcnt(0)
	v_mfma_f32_32x32x16_bf16 v[66:81], v[228:231], v[124:127], v[66:81]
	ds_read_b128 v[172:175], v195 offset:32768
	ds_read_b128 v[228:231], v195 offset:40960
	s_waitcnt lgkmcnt(1)
	v_mfma_f32_32x32x16_bf16 v[82:97], v[172:175], v[120:123], v[82:97]
	s_waitcnt lgkmcnt(0)
	v_mfma_f32_32x32x16_bf16 v[66:81], v[228:231], v[120:123], v[66:81]
	ds_read_b128 v[172:175], v169 offset:32896
	ds_read_b128 v[228:231], v169 offset:41088
	s_waitcnt lgkmcnt(1)
	v_mfma_f32_32x32x16_bf16 v[82:97], v[172:175], v[116:119], v[82:97]
	s_waitcnt lgkmcnt(0)
	v_mfma_f32_32x32x16_bf16 v[66:81], v[228:231], v[116:119], v[66:81]
	ds_read_b128 v[172:175], v193 offset:32896
	ds_read_b128 v[228:231], v193 offset:41088
	s_waitcnt lgkmcnt(1)
	v_mfma_f32_32x32x16_bf16 v[82:97], v[172:175], v[112:115], v[82:97]
	s_waitcnt lgkmcnt(0)
	v_mfma_f32_32x32x16_bf16 v[66:81], v[228:231], v[112:115], v[66:81]
	ds_read_b128 v[172:175], v194 offset:32896
	ds_read_b128 v[228:231], v194 offset:41088
	s_waitcnt lgkmcnt(1)
	v_mfma_f32_32x32x16_bf16 v[82:97], v[172:175], v[108:111], v[82:97]
	s_waitcnt lgkmcnt(0)
	v_mfma_f32_32x32x16_bf16 v[66:81], v[228:231], v[108:111], v[66:81]
	ds_read_b128 v[172:175], v195 offset:32896
	ds_read_b128 v[228:231], v195 offset:41088
	s_waitcnt lgkmcnt(1)
	v_mfma_f32_32x32x16_bf16 v[82:97], v[172:175], v[104:107], v[82:97]
	v_exp_f32_e32 v173, v209
	v_exp_f32_e32 v209, v203
	v_add_f32_e32 v203, 0, v234
	v_add_f32_e32 v203, v249, v203
	v_add_f32_e32 v203, v235, v203
	v_add_f32_e32 v203, v248, v203
	v_add_f32_e32 v203, v236, v203
	v_add_f32_e32 v203, v247, v203
	v_add_f32_e32 v203, v237, v203
	v_add_f32_e32 v203, v246, v203
	v_add_f32_e32 v203, v238, v203
	v_add_f32_e32 v203, v245, v203
	v_add_f32_e32 v203, v239, v203
	v_add_f32_e32 v203, v244, v203
	v_exp_f32_e32 v172, v208
	v_add_f32_e32 v203, v240, v203
	v_add_f32_e32 v203, v243, v203
	v_exp_f32_e32 v174, v223
	v_add_f32_e32 v203, v241, v203
	v_exp_f32_e32 v175, v224
	v_add_f32_e32 v203, v242, v203
	v_exp_f32_e32 v208, v225
	v_add_f32_e32 v203, v172, v203
	v_add_f32_e32 v203, v173, v203
	v_add_f32_e32 v203, v174, v203
	v_add_f32_e32 v203, v175, v203
	v_add_f32_e32 v203, v208, v203
	v_add_f32_e32 v203, v198, v203
	v_add_f32_e32 v203, v201, v203
	v_add_f32_e32 v203, v209, v203
	v_add_f32_e32 v203, v214, v203
	v_add_f32_e32 v203, v205, v203
	s_waitcnt lgkmcnt(0)
	v_mfma_f32_32x32x16_bf16 v[66:81], v[228:231], v[104:107], v[66:81]
	v_add_f32_e32 v203, v206, v203
	v_add_f32_e32 v203, v207, v203
	v_add_f32_e32 v203, v181, v203
	v_add_f32_e32 v203, v215, v203
	v_add_f32_e32 v203, v216, v203
	v_add_f32_e32 v203, v180, v203
	v_mov_b32_e32 v204, v203
	v_cvt_pk_bf16_f32 v148, v234, v249
	v_cvt_pk_bf16_f32 v149, v235, v248
	v_cvt_pk_bf16_f32 v150, v236, v247
	v_cvt_pk_bf16_f32 v151, v237, v246
	v_cvt_pk_bf16_f32 v152, v238, v245
	v_cvt_pk_bf16_f32 v153, v239, v244
	v_cvt_pk_bf16_f32 v154, v240, v243
	v_cvt_pk_bf16_f32 v155, v241, v242
	v_cvt_pk_bf16_f32 v156, v172, v173
	v_cvt_pk_bf16_f32 v157, v174, v175
	v_cvt_pk_bf16_f32 v158, v208, v198
	v_cvt_pk_bf16_f32 v159, v201, v209
	v_cvt_pk_bf16_f32 v160, v214, v205
	v_cvt_pk_bf16_f32 v161, v206, v207
	v_cvt_pk_bf16_f32 v162, v181, v215
	v_cvt_pk_bf16_f32 v163, v216, v180
	s_nop 1
	v_permlane32_swap_b32_e32 v203, v204
	v_permlane32_swap_b32_e32 v148, v150
	v_permlane32_swap_b32_e32 v149, v151
	v_permlane32_swap_b32_e32 v152, v154
	v_permlane32_swap_b32_e32 v153, v155
	v_permlane32_swap_b32_e32 v156, v158
	v_permlane32_swap_b32_e32 v157, v159
	v_permlane32_swap_b32_e32 v160, v162
	v_permlane32_swap_b32_e32 v161, v163
	s_cmp_lt_u32 s3, s2
	s_cselect_b64 s[22:23], -1, 0
	s_cmp_ge_u32 s3, s2
	s_cbranch_scc1 .LBB0_97
	v_add_u32_e32 v100, 0x41, v178
	v_add_u32_e32 v102, 0x61, v178
	v_ashrrev_i32_e32 v101, 31, v100
	v_ashrrev_i32_e32 v103, 31, v102
	v_lshlrev_b64 v[140:141], 8, v[100:101]
	v_lshlrev_b64 v[142:143], 8, v[102:103]
	v_lshl_add_u64 v[100:101], v[170:171], 0, v[140:141]
	v_lshl_add_u64 v[136:137], v[170:171], 0, v[142:143]
	v_lshl_add_u64 v[140:141], v[176:177], 0, v[140:141]
	v_lshl_add_u64 v[144:145], v[176:177], 0, v[142:143]
	global_load_dwordx4 v[100:103], v[100:101], off
	s_nop 0
	global_load_dwordx4 v[136:139], v[136:137], off
	s_nop 0
	global_load_dwordx4 v[140:143], v[140:141], off
	s_nop 0
	global_load_dwordx4 v[144:147], v[144:145], off
